# P1 Z stores and P3a gate stores write-through (sc1): the streamed outputs no longer displace the A/B tiles in L2
# baseline (speedup 1.0000x reference)
.LBB0_533:
	v_lshl_or_b32 v148, s83, 8, v187
	v_ashrrev_i32_e32 v149, 31, v148
	v_lshl_add_u64 v[114:115], v[148:149], 2, s[6:7]
	global_load_dwordx4 v[126:129], v[114:115], off
	global_load_dwordx4 v[122:125], v[114:115], off offset:16
	global_load_dwordx4 v[118:121], v[114:115], off offset:512
	s_nop 0
	global_load_dwordx4 v[114:117], v[114:115], off offset:528
	v_mov_b32_e32 v172, s73
	v_mov_b32_e32 v174, s74
	ds_read2_b32 v[172:173], v172 offset1:1
	ds_read_b32 v176, v174
	v_lshl_add_u32 v178, s50, 8, v184
	v_ashrrev_i32_e32 v179, 31, v178
	v_lshlrev_b64 v[174:175], 13, v[178:179]
	s_waitcnt lgkmcnt(0)
	v_cmp_eq_u32_e32 vcc, s50, v172
	v_lshlrev_b64 v[180:181], 1, v[148:149]
	v_lshl_add_u64 v[148:149], s[36:37], 0, v[174:175]
	v_cndmask_b32_e32 v172, 0, v202, vcc
	v_cmp_ne_u32_e32 vcc, s50, v173
	s_mov_b32 s43, 0x120000
	s_mov_b64 s[58:59], 0x120000
	v_cndmask_b32_e32 v172, v203, v172, vcc
	v_cmp_ne_u32_e32 vcc, s50, v176
	s_nop 1
	v_cndmask_b32_e32 v172, v204, v172, vcc
	v_lshl_add_u32 v174, v172, 2, v186
	ds_read2_b32 v[190:191], v174 offset1:16
	v_lshl_add_u64 v[172:173], v[148:149], 0, v[180:181]
	ds_read2_b32 v[182:183], v174 offset0:32 offset1:48
	ds_read2_b32 v[176:177], v174 offset0:128 offset1:144
	ds_read2_b32 v[174:175], v174 offset0:160 offset1:176
	s_waitcnt vmcnt(0) lgkmcnt(0)
	v_pk_fma_f32 v[144:145], v[144:145], v[190:191], v[128:129] op_sel_hi:[1,0,1]
	v_pk_fma_f32 v[142:143], v[142:143], v[190:191], v[126:127] op_sel_hi:[1,0,1]
	v_pk_fma_f32 v[140:141], v[140:141], v[190:191], v[124:125] op_sel_hi:[1,0,1]
	v_pk_fma_f32 v[138:139], v[138:139], v[190:191], v[122:123] op_sel_hi:[1,0,1]
	v_pk_fma_f32 v[148:149], v[132:133], v[190:191], v[116:117] op_sel_hi:[1,0,1]
	v_pk_fma_f32 v[130:131], v[130:131], v[190:191], v[114:115] op_sel_hi:[1,0,1]
	v_mul_f32_e32 v132, 0xbfb8aa3b, v142
	v_mul_f32_e32 v133, 0xbfb8aa3b, v138
	v_mul_f32_e32 v138, 0xbfb8aa3b, v143
	v_mul_f32_e32 v139, 0xbfb8aa3b, v139
	v_mul_f32_e32 v142, 0xbfb8aa3b, v144
	v_mul_f32_e32 v140, 0xbfb8aa3b, v140
	v_mul_f32_e32 v143, 0xbfb8aa3b, v145
	v_mul_f32_e32 v141, 0xbfb8aa3b, v141
	v_mul_f32_e32 v130, 0xbfb8aa3b, v130
	v_exp_f32_e32 v132, v132
	v_exp_f32_e32 v133, v133
	v_exp_f32_e32 v138, v138
	v_exp_f32_e32 v139, v139
	v_exp_f32_e32 v142, v142
	v_exp_f32_e32 v140, v140
	v_exp_f32_e32 v143, v143
	v_exp_f32_e32 v141, v141
	v_exp_f32_e32 v130, v130
	v_mul_f32_e32 v131, 0xbfb8aa3b, v131
	v_exp_f32_e32 v144, v131
	v_add_f32_e32 v131, 1.0, v132
	v_add_f32_e32 v132, 1.0, v133
	v_add_f32_e32 v133, 1.0, v138
	v_add_f32_e32 v138, 1.0, v139
	v_add_f32_e32 v139, 1.0, v142
	v_add_f32_e32 v140, 1.0, v140
	v_add_f32_e32 v142, 1.0, v143
	v_add_f32_e32 v141, 1.0, v141
	v_pk_fma_f32 v[134:135], v[134:135], v[190:191], v[118:119] op_sel_hi:[1,0,1]
	v_add_f32_e32 v130, 1.0, v130
	v_rcp_f32_e32 v131, v131
	v_rcp_f32_e32 v132, v132
	v_rcp_f32_e32 v133, v133
	v_rcp_f32_e32 v138, v138
	v_rcp_f32_e32 v139, v139
	v_rcp_f32_e32 v140, v140
	v_rcp_f32_e32 v142, v142
	v_rcp_f32_e32 v141, v141
	v_mul_f32_e32 v135, 0xbfb8aa3b, v135
	v_rcp_f32_e32 v130, v130
	v_exp_f32_e32 v135, v135
	v_max_f32_e32 v131, 0x30800000, v131
	v_max_f32_e32 v132, 0x30800000, v132
	v_max_f32_e32 v133, 0x30800000, v133
	v_max_f32_e32 v138, 0x30800000, v138
	v_max_f32_e32 v139, 0x30800000, v139
	v_max_f32_e32 v140, 0x30800000, v140
	v_max_f32_e32 v142, 0x30800000, v142
	v_max_f32_e32 v141, 0x30800000, v141
	v_pk_fma_f32 v[136:137], v[136:137], v[190:191], v[120:121] op_sel_hi:[1,0,1]
	v_max_f32_e32 v143, 0x30800000, v130
	v_cvt_pk_bf16_f32 v130, v131, v133
	v_cvt_pk_bf16_f32 v131, v139, v142
	v_cvt_pk_bf16_f32 v132, v132, v138
	v_cvt_pk_bf16_f32 v133, v140, v141
	v_add_f32_e32 v135, 1.0, v135
	global_store_dwordx4 v[172:173], v[130:133], off sc1
	v_rcp_f32_e32 v135, v135
	v_mul_f32_e32 v134, 0xbfb8aa3b, v134
	v_add_f32_e32 v131, 1.0, v144
	v_mul_f32_e32 v132, 0xbfb8aa3b, v136
	v_mul_f32_e32 v133, 0xbfb8aa3b, v148
	v_rcp_f32_e32 v131, v131
	v_exp_f32_e32 v132, v132
	v_exp_f32_e32 v133, v133
	v_max_f32_e32 v130, 0x30800000, v135
	v_max_f32_e32 v135, 0x30800000, v131
	v_add_f32_e32 v131, 1.0, v132
	v_add_f32_e32 v132, 1.0, v133
	v_mul_f32_e32 v133, 0xbfb8aa3b, v137
	v_mul_f32_e32 v136, 0xbfb8aa3b, v149
	v_exp_f32_e32 v134, v134
	v_exp_f32_e32 v133, v133
	v_exp_f32_e32 v136, v136
	v_rcp_f32_e32 v131, v131
	v_add_f32_e32 v134, 1.0, v134
	v_add_f32_e32 v133, 1.0, v133
	v_add_f32_e32 v136, 1.0, v136
	v_rcp_f32_e32 v134, v134
	v_rcp_f32_e32 v132, v132
	v_rcp_f32_e32 v133, v133
	v_rcp_f32_e32 v136, v136
	v_max_f32_e32 v134, 0x30800000, v134
	v_max_f32_e32 v131, 0x30800000, v131
	v_max_f32_e32 v137, 0x30800000, v132
	v_max_f32_e32 v132, 0x30800000, v133
	v_max_f32_e32 v133, 0x30800000, v136
	v_cvt_pk_bf16_f32 v130, v134, v130
	v_cvt_pk_bf16_f32 v131, v131, v132
	v_cvt_pk_bf16_f32 v132, v143, v135
	v_cvt_pk_bf16_f32 v133, v137, v133
	global_store_dwordx4 v[172:173], v[130:133], off offset:256 sc1
	v_pk_fma_f32 v[94:95], v[94:95], v[182:183], v[126:127] op_sel_hi:[1,0,1]
	v_pk_fma_f32 v[90:91], v[90:91], v[182:183], v[122:123] op_sel_hi:[1,0,1]
	v_mov_b32_e32 v132, v191
	v_pk_fma_f32 v[110:111], v[110:111], v[132:133], v[126:127] op_sel_hi:[1,0,1]
	v_pk_fma_f32 v[106:107], v[106:107], v[132:133], v[122:123] op_sel_hi:[1,0,1]
	v_mul_f32_e32 v111, 0xbfb8aa3b, v111
	v_mul_f32_e32 v106, 0xbfb8aa3b, v106
	v_exp_f32_e32 v106, v106
	v_exp_f32_e32 v111, v111
	v_mul_f32_e32 v107, 0xbfb8aa3b, v107
	v_exp_f32_e32 v107, v107
	v_add_f32_e32 v106, 1.0, v106
	v_add_f32_e32 v111, 1.0, v111
	v_rcp_f32_e32 v106, v106
	v_rcp_f32_e32 v111, v111
	v_pk_fma_f32 v[112:113], v[112:113], v[132:133], v[128:129] op_sel_hi:[1,0,1]
	v_pk_fma_f32 v[108:109], v[108:109], v[132:133], v[124:125] op_sel_hi:[1,0,1]
	v_max_f32_e32 v133, 0x30800000, v106
	v_max_f32_e32 v106, 0x30800000, v111
	v_add_f32_e32 v107, 1.0, v107
	v_mul_f32_e32 v111, 0xbfb8aa3b, v112
	v_rcp_f32_e32 v107, v107
	v_exp_f32_e32 v111, v111
	v_mul_f32_e32 v110, 0xbfb8aa3b, v110
	v_mul_f32_e32 v108, 0xbfb8aa3b, v108
	v_max_f32_e32 v112, 0x30800000, v107
	v_add_f32_e32 v107, 1.0, v111
	v_mul_f32_e32 v111, 0xbfb8aa3b, v113
	v_mul_f32_e32 v109, 0xbfb8aa3b, v109
	v_exp_f32_e32 v110, v110
	v_exp_f32_e32 v108, v108
	v_exp_f32_e32 v111, v111
	v_exp_f32_e32 v109, v109
	v_pk_fma_f32 v[102:103], v[102:103], v[132:133], v[118:119] op_sel_hi:[1,0,1]
	v_pk_fma_f32 v[98:99], v[98:99], v[132:133], v[114:115] op_sel_hi:[1,0,1]
	v_mul_f32_e32 v103, 0xbfb8aa3b, v103
	v_mul_f32_e32 v98, 0xbfb8aa3b, v98
	v_exp_f32_e32 v98, v98
	v_exp_f32_e32 v103, v103
	v_add_f32_e32 v110, 1.0, v110
	v_add_f32_e32 v108, 1.0, v108
	v_add_f32_e32 v111, 1.0, v111
	v_add_f32_e32 v109, 1.0, v109
	v_rcp_f32_e32 v110, v110
	v_rcp_f32_e32 v107, v107
	v_rcp_f32_e32 v108, v108
	v_rcp_f32_e32 v111, v111
	v_rcp_f32_e32 v109, v109
	v_or_b32_e32 v130, 16, v178
	v_add_f32_e32 v98, 1.0, v98
	v_add_f32_e32 v103, 1.0, v103
	v_mul_f32_e32 v99, 0xbfb8aa3b, v99
	v_ashrrev_i32_e32 v131, 31, v130
	v_rcp_f32_e32 v98, v98
	v_rcp_f32_e32 v103, v103
	v_exp_f32_e32 v99, v99
	v_lshlrev_b64 v[130:131], 13, v[130:131]
	v_lshl_add_u64 v[130:131], s[36:37], 0, v[130:131]
	v_max_f32_e32 v110, 0x30800000, v110
	v_max_f32_e32 v107, 0x30800000, v107
	v_max_f32_e32 v113, 0x30800000, v108
	v_max_f32_e32 v108, 0x30800000, v111
	v_max_f32_e32 v109, 0x30800000, v109
	v_lshl_add_u64 v[130:131], v[130:131], 0, v[180:181]
	v_cvt_pk_bf16_f32 v106, v110, v106
	v_cvt_pk_bf16_f32 v107, v107, v108
	v_cvt_pk_bf16_f32 v108, v133, v112
	v_cvt_pk_bf16_f32 v109, v113, v109
	v_pk_fma_f32 v[104:105], v[104:105], v[132:133], v[120:121] op_sel_hi:[1,0,1]
	global_store_dwordx4 v[130:131], v[106:109], off sc1
	v_add_f32_e32 v99, 1.0, v99
	v_rcp_f32_e32 v99, v99
	v_max_f32_e32 v106, 0x30800000, v98
	v_max_f32_e32 v98, 0x30800000, v103
	v_mul_f32_e32 v103, 0xbfb8aa3b, v104
	v_exp_f32_e32 v103, v103
	v_pk_fma_f32 v[100:101], v[100:101], v[132:133], v[116:117] op_sel_hi:[1,0,1]
	v_mul_f32_e32 v102, 0xbfb8aa3b, v102
	v_mul_f32_e32 v100, 0xbfb8aa3b, v100
	v_max_f32_e32 v104, 0x30800000, v99
	v_add_f32_e32 v99, 1.0, v103
	v_mul_f32_e32 v103, 0xbfb8aa3b, v105
	v_mul_f32_e32 v101, 0xbfb8aa3b, v101
	v_exp_f32_e32 v102, v102
	v_exp_f32_e32 v100, v100
	v_exp_f32_e32 v103, v103
	v_exp_f32_e32 v101, v101
	v_mul_f32_e32 v90, 0xbfb8aa3b, v90
	v_mul_f32_e32 v95, 0xbfb8aa3b, v95
	v_exp_f32_e32 v90, v90
	v_exp_f32_e32 v95, v95
	v_add_f32_e32 v102, 1.0, v102
	v_add_f32_e32 v100, 1.0, v100
	v_add_f32_e32 v103, 1.0, v103
	v_add_f32_e32 v101, 1.0, v101
	v_rcp_f32_e32 v102, v102
	v_rcp_f32_e32 v99, v99
	v_rcp_f32_e32 v100, v100
	v_rcp_f32_e32 v103, v103
	v_rcp_f32_e32 v101, v101
	v_add_f32_e32 v90, 1.0, v90
	v_add_f32_e32 v95, 1.0, v95
	v_mul_f32_e32 v91, 0xbfb8aa3b, v91
	v_rcp_f32_e32 v90, v90
	v_rcp_f32_e32 v95, v95
	v_exp_f32_e32 v91, v91
	v_max_f32_e32 v102, 0x30800000, v102
	v_max_f32_e32 v99, 0x30800000, v99
	v_max_f32_e32 v105, 0x30800000, v100
	v_max_f32_e32 v100, 0x30800000, v103
	v_max_f32_e32 v101, 0x30800000, v101
	v_cvt_pk_bf16_f32 v98, v102, v98
	v_cvt_pk_bf16_f32 v99, v99, v100
	v_cvt_pk_bf16_f32 v100, v106, v104
	v_cvt_pk_bf16_f32 v101, v105, v101
	v_pk_fma_f32 v[96:97], v[96:97], v[182:183], v[128:129] op_sel_hi:[1,0,1]
	global_store_dwordx4 v[130:131], v[98:101], off offset:256 sc1
	v_add_f32_e32 v91, 1.0, v91
	v_rcp_f32_e32 v91, v91
	v_max_f32_e32 v100, 0x30800000, v90
	v_max_f32_e32 v90, 0x30800000, v95
	v_mul_f32_e32 v95, 0xbfb8aa3b, v96
	v_exp_f32_e32 v95, v95
	v_pk_fma_f32 v[92:93], v[92:93], v[182:183], v[124:125] op_sel_hi:[1,0,1]
	v_mul_f32_e32 v94, 0xbfb8aa3b, v94
	v_mul_f32_e32 v92, 0xbfb8aa3b, v92
	v_max_f32_e32 v96, 0x30800000, v91
	v_add_f32_e32 v91, 1.0, v95
	v_mul_f32_e32 v95, 0xbfb8aa3b, v97
	v_mul_f32_e32 v93, 0xbfb8aa3b, v93
	v_exp_f32_e32 v94, v94
	v_exp_f32_e32 v92, v92
	v_exp_f32_e32 v95, v95
	v_exp_f32_e32 v93, v93
	v_pk_fma_f32 v[86:87], v[86:87], v[182:183], v[118:119] op_sel_hi:[1,0,1]
	v_pk_fma_f32 v[82:83], v[82:83], v[182:183], v[114:115] op_sel_hi:[1,0,1]
	v_mul_f32_e32 v87, 0xbfb8aa3b, v87
	v_mul_f32_e32 v82, 0xbfb8aa3b, v82
	v_exp_f32_e32 v82, v82
	v_exp_f32_e32 v87, v87
	v_add_f32_e32 v94, 1.0, v94
	v_add_f32_e32 v92, 1.0, v92
	v_add_f32_e32 v95, 1.0, v95
	v_add_f32_e32 v93, 1.0, v93
	v_rcp_f32_e32 v94, v94
	v_rcp_f32_e32 v91, v91
	v_rcp_f32_e32 v92, v92
	v_rcp_f32_e32 v95, v95
	v_rcp_f32_e32 v93, v93
	v_or_b32_e32 v98, 32, v178
	v_add_f32_e32 v82, 1.0, v82
	v_add_f32_e32 v87, 1.0, v87
	v_mul_f32_e32 v83, 0xbfb8aa3b, v83
	v_ashrrev_i32_e32 v99, 31, v98
	v_rcp_f32_e32 v82, v82
	v_rcp_f32_e32 v87, v87
	v_exp_f32_e32 v83, v83
	v_lshlrev_b64 v[98:99], 13, v[98:99]
	v_lshl_add_u64 v[98:99], s[36:37], 0, v[98:99]
	v_max_f32_e32 v94, 0x30800000, v94
	v_max_f32_e32 v91, 0x30800000, v91
	v_max_f32_e32 v97, 0x30800000, v92
	v_max_f32_e32 v92, 0x30800000, v95
	v_max_f32_e32 v93, 0x30800000, v93
	v_lshl_add_u64 v[98:99], v[98:99], 0, v[180:181]
	v_cvt_pk_bf16_f32 v90, v94, v90
	v_cvt_pk_bf16_f32 v91, v91, v92
	v_cvt_pk_bf16_f32 v92, v100, v96
	v_cvt_pk_bf16_f32 v93, v97, v93
	v_pk_fma_f32 v[88:89], v[88:89], v[182:183], v[120:121] op_sel_hi:[1,0,1]
	global_store_dwordx4 v[98:99], v[90:93], off sc1
	v_add_f32_e32 v83, 1.0, v83
	v_rcp_f32_e32 v83, v83
	v_max_f32_e32 v90, 0x30800000, v82
	v_max_f32_e32 v82, 0x30800000, v87
	v_mul_f32_e32 v87, 0xbfb8aa3b, v88
	v_exp_f32_e32 v87, v87
	v_pk_fma_f32 v[84:85], v[84:85], v[182:183], v[116:117] op_sel_hi:[1,0,1]
	v_mul_f32_e32 v86, 0xbfb8aa3b, v86
	v_mul_f32_e32 v84, 0xbfb8aa3b, v84
	v_max_f32_e32 v88, 0x30800000, v83
	v_add_f32_e32 v83, 1.0, v87
	v_mul_f32_e32 v87, 0xbfb8aa3b, v89
	v_mul_f32_e32 v85, 0xbfb8aa3b, v85
	v_exp_f32_e32 v86, v86
	v_exp_f32_e32 v84, v84
	v_exp_f32_e32 v87, v87
	v_exp_f32_e32 v85, v85
	v_add_f32_e32 v86, 1.0, v86
	v_add_f32_e32 v84, 1.0, v84
	v_add_f32_e32 v87, 1.0, v87
	v_add_f32_e32 v85, 1.0, v85
	v_rcp_f32_e32 v86, v86
	v_rcp_f32_e32 v83, v83
	v_rcp_f32_e32 v84, v84
	v_rcp_f32_e32 v87, v87
	v_rcp_f32_e32 v85, v85
	v_max_f32_e32 v86, 0x30800000, v86
	v_max_f32_e32 v83, 0x30800000, v83
	v_max_f32_e32 v89, 0x30800000, v84
	v_max_f32_e32 v84, 0x30800000, v87
	v_max_f32_e32 v85, 0x30800000, v85
	v_cvt_pk_bf16_f32 v82, v86, v82
	v_cvt_pk_bf16_f32 v83, v83, v84
	v_cvt_pk_bf16_f32 v84, v90, v88
	v_cvt_pk_bf16_f32 v85, v89, v85
	global_store_dwordx4 v[98:99], v[82:85], off offset:256 sc1
	v_pk_fma_f32 v[62:63], v[62:63], v[176:177], v[126:127] op_sel_hi:[1,0,1]
	v_pk_fma_f32 v[58:59], v[58:59], v[176:177], v[122:123] op_sel_hi:[1,0,1]
	v_mov_b32_e32 v84, v183
	v_pk_fma_f32 v[78:79], v[78:79], v[84:85], v[126:127] op_sel_hi:[1,0,1]
	v_pk_fma_f32 v[74:75], v[74:75], v[84:85], v[122:123] op_sel_hi:[1,0,1]
	v_mul_f32_e32 v79, 0xbfb8aa3b, v79
	v_mul_f32_e32 v74, 0xbfb8aa3b, v74
	v_exp_f32_e32 v74, v74
	v_exp_f32_e32 v79, v79
	v_mul_f32_e32 v75, 0xbfb8aa3b, v75
	v_exp_f32_e32 v75, v75
	v_add_f32_e32 v74, 1.0, v74
	v_add_f32_e32 v79, 1.0, v79
	v_rcp_f32_e32 v74, v74
	v_rcp_f32_e32 v79, v79
	v_pk_fma_f32 v[80:81], v[80:81], v[84:85], v[128:129] op_sel_hi:[1,0,1]
	v_pk_fma_f32 v[76:77], v[76:77], v[84:85], v[124:125] op_sel_hi:[1,0,1]
	v_max_f32_e32 v85, 0x30800000, v74
	v_max_f32_e32 v74, 0x30800000, v79
	v_add_f32_e32 v75, 1.0, v75
	v_mul_f32_e32 v79, 0xbfb8aa3b, v80
	v_rcp_f32_e32 v75, v75
	v_exp_f32_e32 v79, v79
	v_mul_f32_e32 v78, 0xbfb8aa3b, v78
	v_mul_f32_e32 v76, 0xbfb8aa3b, v76
	v_max_f32_e32 v80, 0x30800000, v75
	v_add_f32_e32 v75, 1.0, v79
	v_mul_f32_e32 v79, 0xbfb8aa3b, v81
	v_mul_f32_e32 v77, 0xbfb8aa3b, v77
	v_exp_f32_e32 v78, v78
	v_exp_f32_e32 v76, v76
	v_exp_f32_e32 v79, v79
	v_exp_f32_e32 v77, v77
	v_pk_fma_f32 v[70:71], v[70:71], v[84:85], v[118:119] op_sel_hi:[1,0,1]
	v_pk_fma_f32 v[66:67], v[66:67], v[84:85], v[114:115] op_sel_hi:[1,0,1]
	v_mul_f32_e32 v71, 0xbfb8aa3b, v71
	v_mul_f32_e32 v66, 0xbfb8aa3b, v66
	v_exp_f32_e32 v66, v66
	v_exp_f32_e32 v71, v71
	v_add_f32_e32 v78, 1.0, v78
	v_add_f32_e32 v76, 1.0, v76
	v_add_f32_e32 v79, 1.0, v79
	v_add_f32_e32 v77, 1.0, v77
	v_rcp_f32_e32 v78, v78
	v_rcp_f32_e32 v75, v75
	v_rcp_f32_e32 v76, v76
	v_rcp_f32_e32 v79, v79
	v_rcp_f32_e32 v77, v77
	v_or_b32_e32 v82, 48, v178
	v_add_f32_e32 v66, 1.0, v66
	v_add_f32_e32 v71, 1.0, v71
	v_mul_f32_e32 v67, 0xbfb8aa3b, v67
	v_ashrrev_i32_e32 v83, 31, v82
	v_rcp_f32_e32 v66, v66
	v_rcp_f32_e32 v71, v71
	v_exp_f32_e32 v67, v67
	v_lshlrev_b64 v[82:83], 13, v[82:83]
	v_lshl_add_u64 v[82:83], s[36:37], 0, v[82:83]
	v_max_f32_e32 v78, 0x30800000, v78
	v_max_f32_e32 v75, 0x30800000, v75
	v_max_f32_e32 v81, 0x30800000, v76
	v_max_f32_e32 v76, 0x30800000, v79
	v_max_f32_e32 v77, 0x30800000, v77
	v_lshl_add_u64 v[82:83], v[82:83], 0, v[180:181]
	v_cvt_pk_bf16_f32 v74, v78, v74
	v_cvt_pk_bf16_f32 v75, v75, v76
	v_cvt_pk_bf16_f32 v76, v85, v80
	v_cvt_pk_bf16_f32 v77, v81, v77
	v_pk_fma_f32 v[72:73], v[72:73], v[84:85], v[120:121] op_sel_hi:[1,0,1]
	global_store_dwordx4 v[82:83], v[74:77], off sc1
	v_add_f32_e32 v67, 1.0, v67
	v_rcp_f32_e32 v67, v67
	v_max_f32_e32 v74, 0x30800000, v66
	v_max_f32_e32 v66, 0x30800000, v71
	v_mul_f32_e32 v71, 0xbfb8aa3b, v72
	v_exp_f32_e32 v71, v71
	v_pk_fma_f32 v[68:69], v[68:69], v[84:85], v[116:117] op_sel_hi:[1,0,1]
	v_mul_f32_e32 v70, 0xbfb8aa3b, v70
	v_mul_f32_e32 v68, 0xbfb8aa3b, v68
	v_max_f32_e32 v72, 0x30800000, v67
	v_add_f32_e32 v67, 1.0, v71
	v_mul_f32_e32 v71, 0xbfb8aa3b, v73
	v_mul_f32_e32 v69, 0xbfb8aa3b, v69
	v_exp_f32_e32 v70, v70
	v_exp_f32_e32 v68, v68
	v_exp_f32_e32 v71, v71
	v_exp_f32_e32 v69, v69
	v_mul_f32_e32 v58, 0xbfb8aa3b, v58
	v_mul_f32_e32 v63, 0xbfb8aa3b, v63
	v_exp_f32_e32 v58, v58
	v_exp_f32_e32 v63, v63
	v_add_f32_e32 v70, 1.0, v70
	v_add_f32_e32 v68, 1.0, v68
	v_add_f32_e32 v71, 1.0, v71
	v_add_f32_e32 v69, 1.0, v69
	v_rcp_f32_e32 v70, v70
	v_rcp_f32_e32 v67, v67
	v_rcp_f32_e32 v68, v68
	v_rcp_f32_e32 v71, v71
	v_rcp_f32_e32 v69, v69
	v_add_f32_e32 v58, 1.0, v58
	v_add_f32_e32 v63, 1.0, v63
	v_mul_f32_e32 v59, 0xbfb8aa3b, v59
	v_rcp_f32_e32 v58, v58
	v_rcp_f32_e32 v63, v63
	v_exp_f32_e32 v59, v59
	v_max_f32_e32 v70, 0x30800000, v70
	v_max_f32_e32 v67, 0x30800000, v67
	v_max_f32_e32 v73, 0x30800000, v68
	v_max_f32_e32 v68, 0x30800000, v71
	v_max_f32_e32 v69, 0x30800000, v69
	v_cvt_pk_bf16_f32 v66, v70, v66
	v_cvt_pk_bf16_f32 v67, v67, v68
	v_cvt_pk_bf16_f32 v68, v74, v72
	v_cvt_pk_bf16_f32 v69, v73, v69
	v_pk_fma_f32 v[64:65], v[64:65], v[176:177], v[128:129] op_sel_hi:[1,0,1]
	global_store_dwordx4 v[82:83], v[66:69], off offset:256 sc1
	v_add_f32_e32 v59, 1.0, v59
	v_rcp_f32_e32 v59, v59
	v_max_f32_e32 v68, 0x30800000, v58
	v_max_f32_e32 v58, 0x30800000, v63
	v_mul_f32_e32 v63, 0xbfb8aa3b, v64
	v_exp_f32_e32 v63, v63
	v_mul_f32_e32 v62, 0xbfb8aa3b, v62
	v_pk_fma_f32 v[60:61], v[60:61], v[176:177], v[124:125] op_sel_hi:[1,0,1]
	v_exp_f32_e32 v62, v62
	v_mul_f32_e32 v60, 0xbfb8aa3b, v60
	v_max_f32_e32 v64, 0x30800000, v59
	v_add_f32_e32 v59, 1.0, v63
	v_mul_f32_e32 v63, 0xbfb8aa3b, v65
	v_mul_f32_e32 v61, 0xbfb8aa3b, v61
	v_exp_f32_e32 v60, v60
	v_exp_f32_e32 v63, v63
	v_exp_f32_e32 v61, v61
	v_pk_fma_f32 v[54:55], v[54:55], v[176:177], v[118:119] op_sel_hi:[1,0,1]
	v_pk_fma_f32 v[50:51], v[50:51], v[176:177], v[114:115] op_sel_hi:[1,0,1]
	v_mul_f32_e32 v55, 0xbfb8aa3b, v55
	v_mul_f32_e32 v50, 0xbfb8aa3b, v50
	v_exp_f32_e32 v50, v50
	v_exp_f32_e32 v55, v55
	v_add_f32_e32 v62, 1.0, v62
	v_rcp_f32_e32 v62, v62
	v_add_f32_e32 v60, 1.0, v60
	v_add_f32_e32 v63, 1.0, v63
	v_add_f32_e32 v61, 1.0, v61
	v_rcp_f32_e32 v59, v59
	v_rcp_f32_e32 v60, v60
	v_rcp_f32_e32 v63, v63
	v_rcp_f32_e32 v61, v61
	v_add_f32_e32 v50, 1.0, v50
	v_add_f32_e32 v55, 1.0, v55
	v_mul_f32_e32 v51, 0xbfb8aa3b, v51
	v_rcp_f32_e32 v50, v50
	v_rcp_f32_e32 v55, v55
	v_exp_f32_e32 v51, v51
	v_max_f32_e32 v62, 0x30800000, v62
	v_max_f32_e32 v59, 0x30800000, v59
	v_max_f32_e32 v65, 0x30800000, v60
	v_max_f32_e32 v60, 0x30800000, v63
	v_max_f32_e32 v61, 0x30800000, v61
	v_cvt_pk_bf16_f32 v58, v62, v58
	v_add_co_u32_e32 v62, vcc, s72, v172
	v_cvt_pk_bf16_f32 v59, v59, v60
	v_cvt_pk_bf16_f32 v60, v68, v64
	v_cvt_pk_bf16_f32 v61, v65, v61
	v_addc_co_u32_e32 v63, vcc, 0, v173, vcc
	v_pk_fma_f32 v[56:57], v[56:57], v[176:177], v[120:121] op_sel_hi:[1,0,1]
	global_store_dwordx4 v[62:63], v[58:61], off sc1
	v_add_f32_e32 v51, 1.0, v51
	v_rcp_f32_e32 v51, v51
	v_max_f32_e32 v58, 0x30800000, v50
	v_max_f32_e32 v50, 0x30800000, v55
	v_mul_f32_e32 v55, 0xbfb8aa3b, v56
	v_exp_f32_e32 v55, v55
	v_pk_fma_f32 v[52:53], v[52:53], v[176:177], v[116:117] op_sel_hi:[1,0,1]
	v_mul_f32_e32 v54, 0xbfb8aa3b, v54
	v_mul_f32_e32 v52, 0xbfb8aa3b, v52
	v_max_f32_e32 v56, 0x30800000, v51
	v_add_f32_e32 v51, 1.0, v55
	v_mul_f32_e32 v55, 0xbfb8aa3b, v57
	v_mul_f32_e32 v53, 0xbfb8aa3b, v53
	v_exp_f32_e32 v54, v54
	v_exp_f32_e32 v52, v52
	v_exp_f32_e32 v55, v55
	v_exp_f32_e32 v53, v53
	v_add_f32_e32 v54, 1.0, v54
	v_add_f32_e32 v52, 1.0, v52
	v_add_f32_e32 v55, 1.0, v55
	v_add_f32_e32 v53, 1.0, v53
	v_rcp_f32_e32 v54, v54
	v_rcp_f32_e32 v51, v51
	v_rcp_f32_e32 v52, v52
	v_rcp_f32_e32 v55, v55
	v_rcp_f32_e32 v53, v53
	v_max_f32_e32 v54, 0x30800000, v54
	v_max_f32_e32 v51, 0x30800000, v51
	v_max_f32_e32 v57, 0x30800000, v52
	v_max_f32_e32 v52, 0x30800000, v55
	v_max_f32_e32 v53, 0x30800000, v53
	v_lshl_add_u64 v[66:67], v[172:173], 0, s[56:57]
	v_cvt_pk_bf16_f32 v50, v54, v50
	v_cvt_pk_bf16_f32 v51, v51, v52
	v_cvt_pk_bf16_f32 v52, v58, v56
	v_cvt_pk_bf16_f32 v53, v57, v53
	global_store_dwordx4 v[66:67], v[50:53], off offset:256 sc1
	v_pk_fma_f32 v[30:31], v[30:31], v[174:175], v[126:127] op_sel_hi:[1,0,1]
	v_pk_fma_f32 v[26:27], v[26:27], v[174:175], v[122:123] op_sel_hi:[1,0,1]
	v_mov_b32_e32 v52, v177
	v_pk_fma_f32 v[46:47], v[46:47], v[52:53], v[126:127] op_sel_hi:[1,0,1]
	v_pk_fma_f32 v[42:43], v[42:43], v[52:53], v[122:123] op_sel_hi:[1,0,1]
	v_mul_f32_e32 v47, 0xbfb8aa3b, v47
	v_mul_f32_e32 v42, 0xbfb8aa3b, v42
	v_exp_f32_e32 v42, v42
	v_exp_f32_e32 v47, v47
	v_mul_f32_e32 v43, 0xbfb8aa3b, v43
	v_exp_f32_e32 v43, v43
	v_add_f32_e32 v42, 1.0, v42
	v_add_f32_e32 v47, 1.0, v47
	v_rcp_f32_e32 v42, v42
	v_rcp_f32_e32 v47, v47
	v_pk_fma_f32 v[48:49], v[48:49], v[52:53], v[128:129] op_sel_hi:[1,0,1]
	v_pk_fma_f32 v[44:45], v[44:45], v[52:53], v[124:125] op_sel_hi:[1,0,1]
	v_max_f32_e32 v53, 0x30800000, v42
	v_max_f32_e32 v42, 0x30800000, v47
	v_add_f32_e32 v43, 1.0, v43
	v_mul_f32_e32 v47, 0xbfb8aa3b, v48
	v_rcp_f32_e32 v43, v43
	v_exp_f32_e32 v47, v47
	v_mul_f32_e32 v46, 0xbfb8aa3b, v46
	v_exp_f32_e32 v46, v46
	v_mul_f32_e32 v44, 0xbfb8aa3b, v44
	v_max_f32_e32 v48, 0x30800000, v43
	v_add_f32_e32 v43, 1.0, v47
	v_mul_f32_e32 v47, 0xbfb8aa3b, v49
	v_mul_f32_e32 v45, 0xbfb8aa3b, v45
	v_exp_f32_e32 v44, v44
	v_exp_f32_e32 v47, v47
	v_exp_f32_e32 v45, v45
	v_pk_fma_f32 v[38:39], v[38:39], v[52:53], v[118:119] op_sel_hi:[1,0,1]
	v_pk_fma_f32 v[34:35], v[34:35], v[52:53], v[114:115] op_sel_hi:[1,0,1]
	v_mul_f32_e32 v39, 0xbfb8aa3b, v39
	v_mul_f32_e32 v34, 0xbfb8aa3b, v34
	v_exp_f32_e32 v34, v34
	v_exp_f32_e32 v39, v39
	v_add_f32_e32 v46, 1.0, v46
	v_rcp_f32_e32 v46, v46
	v_add_f32_e32 v44, 1.0, v44
	v_add_f32_e32 v47, 1.0, v47
	v_add_f32_e32 v45, 1.0, v45
	v_rcp_f32_e32 v43, v43
	v_rcp_f32_e32 v44, v44
	v_rcp_f32_e32 v47, v47
	v_rcp_f32_e32 v45, v45
	v_add_f32_e32 v34, 1.0, v34
	v_add_f32_e32 v39, 1.0, v39
	v_mul_f32_e32 v35, 0xbfb8aa3b, v35
	v_rcp_f32_e32 v34, v34
	v_rcp_f32_e32 v39, v39
	v_exp_f32_e32 v35, v35
	v_max_f32_e32 v46, 0x30800000, v46
	v_max_f32_e32 v43, 0x30800000, v43
	v_max_f32_e32 v49, 0x30800000, v44
	v_max_f32_e32 v44, 0x30800000, v47
	v_max_f32_e32 v45, 0x30800000, v45
	v_cvt_pk_bf16_f32 v42, v46, v42
	v_add_co_u32_e32 v46, vcc, s43, v172
	v_cvt_pk_bf16_f32 v43, v43, v44
	v_cvt_pk_bf16_f32 v44, v53, v48
	v_cvt_pk_bf16_f32 v45, v49, v45
	v_addc_co_u32_e32 v47, vcc, 0, v173, vcc
	v_pk_fma_f32 v[40:41], v[40:41], v[52:53], v[120:121] op_sel_hi:[1,0,1]
	global_store_dwordx4 v[46:47], v[42:45], off sc1
	v_add_f32_e32 v35, 1.0, v35
	v_rcp_f32_e32 v35, v35
	v_max_f32_e32 v42, 0x30800000, v34
	v_max_f32_e32 v34, 0x30800000, v39
	v_mul_f32_e32 v39, 0xbfb8aa3b, v40
	v_exp_f32_e32 v39, v39
	v_pk_fma_f32 v[36:37], v[36:37], v[52:53], v[116:117] op_sel_hi:[1,0,1]
	v_mul_f32_e32 v38, 0xbfb8aa3b, v38
	v_mul_f32_e32 v36, 0xbfb8aa3b, v36
	v_max_f32_e32 v40, 0x30800000, v35
	v_add_f32_e32 v35, 1.0, v39
	v_mul_f32_e32 v39, 0xbfb8aa3b, v41
	v_mul_f32_e32 v37, 0xbfb8aa3b, v37
	v_exp_f32_e32 v38, v38
	v_exp_f32_e32 v36, v36
	v_exp_f32_e32 v39, v39
	v_exp_f32_e32 v37, v37
	v_mul_f32_e32 v26, 0xbfb8aa3b, v26
	v_mul_f32_e32 v31, 0xbfb8aa3b, v31
	v_exp_f32_e32 v26, v26
	v_exp_f32_e32 v31, v31
	v_add_f32_e32 v38, 1.0, v38
	v_add_f32_e32 v36, 1.0, v36
	v_add_f32_e32 v39, 1.0, v39
	v_add_f32_e32 v37, 1.0, v37
	v_rcp_f32_e32 v38, v38
	v_rcp_f32_e32 v35, v35
	v_rcp_f32_e32 v36, v36
	v_rcp_f32_e32 v39, v39
	v_rcp_f32_e32 v37, v37
	v_add_f32_e32 v26, 1.0, v26
	v_add_f32_e32 v31, 1.0, v31
	v_mul_f32_e32 v27, 0xbfb8aa3b, v27
	v_rcp_f32_e32 v26, v26
	v_rcp_f32_e32 v31, v31
	v_exp_f32_e32 v27, v27
	v_max_f32_e32 v38, 0x30800000, v38
	v_max_f32_e32 v35, 0x30800000, v35
	v_max_f32_e32 v41, 0x30800000, v36
	v_max_f32_e32 v36, 0x30800000, v39
	v_max_f32_e32 v37, 0x30800000, v37
	v_lshl_add_u64 v[50:51], v[172:173], 0, s[58:59]
	v_cvt_pk_bf16_f32 v34, v38, v34
	v_cvt_pk_bf16_f32 v35, v35, v36
	v_cvt_pk_bf16_f32 v36, v42, v40
	v_cvt_pk_bf16_f32 v37, v41, v37
	v_pk_fma_f32 v[32:33], v[32:33], v[174:175], v[128:129] op_sel_hi:[1,0,1]
	global_store_dwordx4 v[50:51], v[34:37], off offset:256 sc1
	v_add_f32_e32 v27, 1.0, v27
	v_rcp_f32_e32 v27, v27
	v_max_f32_e32 v36, 0x30800000, v26
	v_max_f32_e32 v26, 0x30800000, v31
	v_mul_f32_e32 v31, 0xbfb8aa3b, v32
	v_exp_f32_e32 v31, v31
	v_mul_f32_e32 v30, 0xbfb8aa3b, v30
	v_pk_fma_f32 v[28:29], v[28:29], v[174:175], v[124:125] op_sel_hi:[1,0,1]
	v_exp_f32_e32 v30, v30
	v_mul_f32_e32 v28, 0xbfb8aa3b, v28
	v_max_f32_e32 v32, 0x30800000, v27
	v_add_f32_e32 v27, 1.0, v31
	v_mul_f32_e32 v31, 0xbfb8aa3b, v33
	v_mul_f32_e32 v29, 0xbfb8aa3b, v29
	v_exp_f32_e32 v28, v28
	v_exp_f32_e32 v31, v31
	v_exp_f32_e32 v29, v29
	v_pk_fma_f32 v[22:23], v[22:23], v[174:175], v[118:119] op_sel_hi:[1,0,1]
	v_pk_fma_f32 v[18:19], v[18:19], v[174:175], v[114:115] op_sel_hi:[1,0,1]
	v_mul_f32_e32 v23, 0xbfb8aa3b, v23
	v_mul_f32_e32 v18, 0xbfb8aa3b, v18
	v_exp_f32_e32 v18, v18
	v_exp_f32_e32 v23, v23
	v_add_f32_e32 v30, 1.0, v30
	v_rcp_f32_e32 v30, v30
	v_add_f32_e32 v28, 1.0, v28
	v_add_f32_e32 v31, 1.0, v31
	v_add_f32_e32 v29, 1.0, v29
	v_rcp_f32_e32 v27, v27
	v_rcp_f32_e32 v28, v28
	v_rcp_f32_e32 v31, v31
	v_rcp_f32_e32 v29, v29
	v_add_f32_e32 v18, 1.0, v18
	v_add_f32_e32 v23, 1.0, v23
	v_mul_f32_e32 v19, 0xbfb8aa3b, v19
	v_rcp_f32_e32 v18, v18
	v_rcp_f32_e32 v23, v23
	v_exp_f32_e32 v19, v19
	v_max_f32_e32 v30, 0x30800000, v30
	s_mov_b32 s43, 0x140000
	v_max_f32_e32 v27, 0x30800000, v27
	v_max_f32_e32 v33, 0x30800000, v28
	v_max_f32_e32 v28, 0x30800000, v31
	v_max_f32_e32 v29, 0x30800000, v29
	v_cvt_pk_bf16_f32 v26, v30, v26
	v_add_co_u32_e32 v30, vcc, s43, v172
	v_cvt_pk_bf16_f32 v27, v27, v28
	v_cvt_pk_bf16_f32 v28, v36, v32
	v_cvt_pk_bf16_f32 v29, v33, v29
	v_addc_co_u32_e32 v31, vcc, 0, v173, vcc
	v_pk_fma_f32 v[24:25], v[24:25], v[174:175], v[120:121] op_sel_hi:[1,0,1]
	global_store_dwordx4 v[30:31], v[26:29], off sc1
	v_add_f32_e32 v19, 1.0, v19
	v_rcp_f32_e32 v19, v19
	v_max_f32_e32 v26, 0x30800000, v18
	v_max_f32_e32 v18, 0x30800000, v23
	v_mul_f32_e32 v23, 0xbfb8aa3b, v24
	v_exp_f32_e32 v23, v23
	v_pk_fma_f32 v[20:21], v[20:21], v[174:175], v[116:117] op_sel_hi:[1,0,1]
	v_mul_f32_e32 v22, 0xbfb8aa3b, v22
	v_mul_f32_e32 v20, 0xbfb8aa3b, v20
	v_max_f32_e32 v24, 0x30800000, v19
	v_add_f32_e32 v19, 1.0, v23
	v_mul_f32_e32 v23, 0xbfb8aa3b, v25
	v_mul_f32_e32 v21, 0xbfb8aa3b, v21
	v_exp_f32_e32 v22, v22
	v_exp_f32_e32 v20, v20
	v_exp_f32_e32 v23, v23
	v_exp_f32_e32 v21, v21
	v_add_f32_e32 v22, 1.0, v22
	v_add_f32_e32 v20, 1.0, v20
	v_add_f32_e32 v23, 1.0, v23
	v_add_f32_e32 v21, 1.0, v21
	v_rcp_f32_e32 v22, v22
	v_rcp_f32_e32 v19, v19
	v_rcp_f32_e32 v20, v20
	v_rcp_f32_e32 v23, v23
	v_rcp_f32_e32 v21, v21
	s_mov_b64 s[58:59], 0x140000
	v_max_f32_e32 v22, 0x30800000, v22
	v_max_f32_e32 v19, 0x30800000, v19
	v_max_f32_e32 v25, 0x30800000, v20
	v_max_f32_e32 v20, 0x30800000, v23
	v_max_f32_e32 v21, 0x30800000, v21
	v_lshl_add_u64 v[34:35], v[172:173], 0, s[58:59]
	v_cvt_pk_bf16_f32 v18, v22, v18
	v_cvt_pk_bf16_f32 v19, v19, v20
	v_cvt_pk_bf16_f32 v20, v26, v24
	v_cvt_pk_bf16_f32 v21, v25, v21
	global_store_dwordx4 v[34:35], v[18:21], off offset:256 sc1
	s_mov_b32 s43, 0x160000
	s_mov_b64 s[58:59], 0x160000
	v_mov_b32_e32 v20, v175
	v_pk_fma_f32 v[14:15], v[14:15], v[20:21], v[126:127] op_sel_hi:[1,0,1]
	v_pk_fma_f32 v[10:11], v[10:11], v[20:21], v[122:123] op_sel_hi:[1,0,1]
	v_mul_f32_e32 v15, 0xbfb8aa3b, v15
	v_mul_f32_e32 v10, 0xbfb8aa3b, v10
	v_exp_f32_e32 v10, v10
	v_exp_f32_e32 v15, v15
	v_mul_f32_e32 v11, 0xbfb8aa3b, v11
	v_exp_f32_e32 v11, v11
	v_add_f32_e32 v10, 1.0, v10
	v_add_f32_e32 v15, 1.0, v15
	v_rcp_f32_e32 v10, v10
	v_rcp_f32_e32 v15, v15
	v_pk_fma_f32 v[16:17], v[16:17], v[20:21], v[128:129] op_sel_hi:[1,0,1]
	v_pk_fma_f32 v[12:13], v[12:13], v[20:21], v[124:125] op_sel_hi:[1,0,1]
	v_max_f32_e32 v21, 0x30800000, v10
	v_max_f32_e32 v10, 0x30800000, v15
	v_add_f32_e32 v11, 1.0, v11
	v_mul_f32_e32 v15, 0xbfb8aa3b, v16
	v_rcp_f32_e32 v11, v11
	v_exp_f32_e32 v15, v15
	v_mul_f32_e32 v14, 0xbfb8aa3b, v14
	v_exp_f32_e32 v14, v14
	v_mul_f32_e32 v12, 0xbfb8aa3b, v12
	v_max_f32_e32 v16, 0x30800000, v11
	v_add_f32_e32 v11, 1.0, v15
	v_mul_f32_e32 v15, 0xbfb8aa3b, v17
	v_mul_f32_e32 v13, 0xbfb8aa3b, v13
	v_exp_f32_e32 v12, v12
	v_exp_f32_e32 v15, v15
	v_exp_f32_e32 v13, v13
	v_pk_fma_f32 v[6:7], v[6:7], v[20:21], v[118:119] op_sel_hi:[1,0,1]
	v_pk_fma_f32 v[2:3], v[2:3], v[20:21], v[114:115] op_sel_hi:[1,0,1]
	v_mul_f32_e32 v7, 0xbfb8aa3b, v7
	v_mul_f32_e32 v2, 0xbfb8aa3b, v2
	v_exp_f32_e32 v2, v2
	v_exp_f32_e32 v7, v7
	v_add_f32_e32 v14, 1.0, v14
	v_rcp_f32_e32 v14, v14
	v_add_f32_e32 v12, 1.0, v12
	v_add_f32_e32 v15, 1.0, v15
	v_add_f32_e32 v13, 1.0, v13
	v_rcp_f32_e32 v11, v11
	v_rcp_f32_e32 v12, v12
	v_rcp_f32_e32 v15, v15
	v_rcp_f32_e32 v13, v13
	v_add_f32_e32 v2, 1.0, v2
	v_add_f32_e32 v7, 1.0, v7
	v_mul_f32_e32 v3, 0xbfb8aa3b, v3
	v_rcp_f32_e32 v2, v2
	v_rcp_f32_e32 v7, v7
	v_exp_f32_e32 v3, v3
	v_max_f32_e32 v14, 0x30800000, v14
	v_max_f32_e32 v11, 0x30800000, v11
	v_max_f32_e32 v17, 0x30800000, v12
	v_max_f32_e32 v12, 0x30800000, v15
	v_max_f32_e32 v13, 0x30800000, v13
	v_cvt_pk_bf16_f32 v10, v14, v10
	v_add_co_u32_e32 v14, vcc, s43, v172
	v_cvt_pk_bf16_f32 v11, v11, v12
	v_cvt_pk_bf16_f32 v12, v21, v16
	v_cvt_pk_bf16_f32 v13, v17, v13
	v_addc_co_u32_e32 v15, vcc, 0, v173, vcc
	v_pk_fma_f32 v[8:9], v[8:9], v[20:21], v[120:121] op_sel_hi:[1,0,1]
	global_store_dwordx4 v[14:15], v[10:13], off sc1
	v_add_f32_e32 v3, 1.0, v3
	v_rcp_f32_e32 v3, v3
	v_max_f32_e32 v10, 0x30800000, v2
	v_max_f32_e32 v2, 0x30800000, v7
	v_mul_f32_e32 v7, 0xbfb8aa3b, v8
	v_exp_f32_e32 v7, v7
	v_pk_fma_f32 v[4:5], v[4:5], v[20:21], v[116:117] op_sel_hi:[1,0,1]
	v_mul_f32_e32 v6, 0xbfb8aa3b, v6
	v_mul_f32_e32 v4, 0xbfb8aa3b, v4
	v_max_f32_e32 v8, 0x30800000, v3
	v_add_f32_e32 v3, 1.0, v7
	v_mul_f32_e32 v7, 0xbfb8aa3b, v9
	v_mul_f32_e32 v5, 0xbfb8aa3b, v5
	v_exp_f32_e32 v6, v6
	v_exp_f32_e32 v4, v4
	v_exp_f32_e32 v7, v7
	v_exp_f32_e32 v5, v5
	v_add_f32_e32 v6, 1.0, v6
	v_add_f32_e32 v4, 1.0, v4
	v_add_f32_e32 v7, 1.0, v7
	v_add_f32_e32 v5, 1.0, v5
	v_rcp_f32_e32 v6, v6
	v_rcp_f32_e32 v3, v3
	v_rcp_f32_e32 v4, v4
	v_rcp_f32_e32 v7, v7
	v_rcp_f32_e32 v5, v5
	v_max_f32_e32 v6, 0x30800000, v6
	v_max_f32_e32 v3, 0x30800000, v3
	v_max_f32_e32 v9, 0x30800000, v4
	v_max_f32_e32 v4, 0x30800000, v7
	v_max_f32_e32 v5, 0x30800000, v5
	v_lshl_add_u64 v[18:19], v[172:173], 0, s[58:59]
	v_cvt_pk_bf16_f32 v2, v6, v2
	v_cvt_pk_bf16_f32 v3, v3, v4
	v_cvt_pk_bf16_f32 v4, v10, v8
	v_cvt_pk_bf16_f32 v5, v9, v5
	s_andn2_b64 vcc, exec, s[2:3]
	s_mov_b64 s[2:3], -1
	global_store_dwordx4 v[18:19], v[2:5], off offset:256 sc1
	s_cbranch_vccnz .LBB0_521
	s_andn2_b64 vcc, exec, s[0:1]
	s_cbranch_vccnz .LBB0_520
	s_barrier
	s_branch .LBB0_520
